# v46 + grid barrier: waiting workgroups poll the top-level generation word directly (no per-XCD release hop), XCD leader drops the per-XCD generation publish
# speedup vs baseline: 1.0008x; 1.0008x over previous
; __device__ __forceinline__ unsigned xb_ld(unsigned* p)              { return __hip_atomic_load(p, __ATOMIC_RELAXED, __HIP_MEMORY_SCOPE_AGENT); }
; __device__ __forceinline__ unsigned xb_add(unsigned* p, unsigned v) { return __hip_atomic_fetch_add(p, v, __ATOMIC_RELAXED, __HIP_MEMORY_SCOPE_AGENT); }
; #define XB_SPIN(cond, bar) do { unsigned _sp = 0; while (cond) { __builtin_amdgcn_s_sleep(1); \
;     if ((++_sp & 255u) == 0u) { if (xb_ld(&(bar)[XB_TMO])) break; if (_sp > XB_SPIN_CAP) { atomicAdd(&(bar)[XB_TMO], 1u); break; } } } } while (0)
; __device__ __forceinline__ void xcd_barrier(const XcdBarrier& b, const int wv) {
;     ...
;         const unsigned old = xb_add(&bar[XB_XSUB(bx)], 1u);
;         const unsigned gen = old / nloc;
;         if (old + 1u == (gen + 1u) * nloc) {
;             __builtin_amdgcn_fence(__ATOMIC_RELEASE, "agent");
;             asm volatile("s_waitcnt vmcnt(0)" ::: "memory");
;             const unsigned og = xb_add(&bar[XB_TOP], 1u);
;             const unsigned tg = og / nx;
;             if (og + 1u == (tg + 1u) * nx) xb_add(&bar[XB_TOPGEN], 1u);
;             else XB_SPIN(xb_ld(&bar[XB_TOPGEN]) == tg, bar);
;             __builtin_amdgcn_fence(__ATOMIC_ACQUIRE, "agent");
;             xb_add(&bar[XB_XGEN(bx)], 1u);
;             asm volatile("s_waitcnt vmcnt(0)" ::: "memory");
;         } else {
;             XB_SPIN(xb_ld(&bar[XB_XGEN(bx)]) == gen, bar);
.LBB0_148:
	s_lshl_b32 s0, s0, 6
	s_add_i32 s6, s0, 0x500
	s_mov_b32 s7, 0
	s_lshl_b64 s[4:5], s[6:7], 2
	s_add_u32 s4, s46, s4
	s_addc_u32 s5, s47, s5
	v_mov_b32_e32 v1, 1
	v_mov_b64_e32 v[4:5], s[4:5]
	flat_atomic_add v1, v[4:5], v1 sc0
	v_cvt_f32_u32_e32 v3, v2
	v_sub_u32_e32 v4, 0, v2
	v_rcp_iflag_f32_e32 v3, v3
	s_nop 0
	v_mul_f32_e32 v3, 0x4f7ffffe, v3
	v_cvt_u32_f32_e32 v3, v3
	v_mul_lo_u32 v4, v4, v3
	v_mul_hi_u32 v4, v3, v4
	v_add_u32_e32 v3, v3, v4
	s_waitcnt vmcnt(0) lgkmcnt(0)
	v_mul_hi_u32 v3, v1, v3
	v_mul_lo_u32 v5, v3, v2
	v_add_u32_e32 v4, 1, v1
	v_sub_u32_e32 v1, v1, v5
	v_add_u32_e32 v6, 1, v3
	v_cmp_ge_u32_e32 vcc, v1, v2
	v_sub_u32_e32 v5, v1, v2
	s_nop 0
	v_cndmask_b32_e32 v3, v3, v6, vcc
	v_cndmask_b32_e32 v1, v1, v5, vcc
	v_add_u32_e32 v5, 1, v3
	v_cmp_ge_u32_e32 vcc, v1, v2
	s_nop 1
	v_cndmask_b32_e32 v1, v3, v5, vcc
	v_mad_u64_u32 v[2:3], s[4:5], v2, v1, v[2:3]
	v_cmp_ne_u32_e32 vcc, v4, v2
	s_and_saveexec_b64 s[4:5], vcc
	s_xor_b64 s[4:5], exec, s[4:5]
	s_cbranch_execz .LBB0_161
	s_add_i32 s6, s0, 0x900
	s_lshl_b64 s[6:7], s[6:7], 2
	s_add_u32 s8, s46, 0x3500
	s_addc_u32 s9, s47, 0
	v_mov_b64_e32 v[2:3], s[8:9]
	flat_load_dword v0, v[2:3] sc1
	s_waitcnt vmcnt(0) lgkmcnt(0)
	v_cmp_eq_u32_e32 vcc, v0, v1
	s_and_saveexec_b64 s[6:7], vcc
	s_cbranch_execz .LBB0_160
	s_mov_b32 s1, 1
	s_mov_b64 s[10:11], 0
	s_branch .LBB0_152

; __device__ __forceinline__ unsigned xb_add(unsigned* p, unsigned v) { return __hip_atomic_fetch_add(p, v, __ATOMIC_RELAXED, __HIP_MEMORY_SCOPE_AGENT); }
; __device__ __forceinline__ void xcd_barrier(const XcdBarrier& b, const int wv) {
;     ...
;             __builtin_amdgcn_fence(__ATOMIC_ACQUIRE, "agent");
;             xb_add(&bar[XB_XGEN(bx)], 1u);
;             asm volatile("s_waitcnt vmcnt(0)" ::: "memory");
.LBB0_176:
	s_or_b64 exec, exec, s[6:7]
	s_addk_i32 s0, 0x900
	s_mov_b32 s1, 0
	s_lshl_b64 s[0:1], s[0:1], 2
	s_add_u32 s0, s46, s0
	s_addc_u32 s1, s47, s1
	v_mov_b32_e32 v2, 1
	v_mov_b64_e32 v[0:1], s[0:1]
	s_waitcnt vmcnt(0) lgkmcnt(0)
	buffer_inv sc1
	s_waitcnt vmcnt(0)

; __device__ __forceinline__ unsigned xb_ld(unsigned* p)              { return __hip_atomic_load(p, __ATOMIC_RELAXED, __HIP_MEMORY_SCOPE_AGENT); }
; __device__ __forceinline__ unsigned xb_add(unsigned* p, unsigned v) { return __hip_atomic_fetch_add(p, v, __ATOMIC_RELAXED, __HIP_MEMORY_SCOPE_AGENT); }
; #define XB_SPIN(cond, bar) do { unsigned _sp = 0; while (cond) { __builtin_amdgcn_s_sleep(1); \
;     if ((++_sp & 255u) == 0u) { if (xb_ld(&(bar)[XB_TMO])) break; if (_sp > XB_SPIN_CAP) { atomicAdd(&(bar)[XB_TMO], 1u); break; } } } } while (0)
; __device__ __forceinline__ void xcd_barrier(const XcdBarrier& b, const int wv) {
;     ...
;         const unsigned old = xb_add(&bar[XB_XSUB(bx)], 1u);
;         const unsigned gen = old / nloc;
;         if (old + 1u == (gen + 1u) * nloc) {
;             __builtin_amdgcn_fence(__ATOMIC_RELEASE, "agent");
;             asm volatile("s_waitcnt vmcnt(0)" ::: "memory");
;             const unsigned og = xb_add(&bar[XB_TOP], 1u);
;             const unsigned tg = og / nx;
;             if (og + 1u == (tg + 1u) * nx) xb_add(&bar[XB_TOPGEN], 1u);
;             else XB_SPIN(xb_ld(&bar[XB_TOPGEN]) == tg, bar);
;             __builtin_amdgcn_fence(__ATOMIC_ACQUIRE, "agent");
;             xb_add(&bar[XB_XGEN(bx)], 1u);
;             asm volatile("s_waitcnt vmcnt(0)" ::: "memory");
;         } else {
;             XB_SPIN(xb_ld(&bar[XB_XGEN(bx)]) == gen, bar);
.LBB0_220:
	s_lshl_b32 s0, s0, 6
	s_add_i32 s6, s0, 0x500
	s_mov_b32 s7, 0
	s_lshl_b64 s[4:5], s[6:7], 2
	s_add_u32 s4, s40, s4
	s_addc_u32 s5, s41, s5
	v_mov_b32_e32 v1, 1
	v_mov_b64_e32 v[4:5], s[4:5]
	flat_atomic_add v1, v[4:5], v1 sc0
	v_cvt_f32_u32_e32 v3, v2
	v_sub_u32_e32 v4, 0, v2
	v_rcp_iflag_f32_e32 v3, v3
	s_nop 0
	v_mul_f32_e32 v3, 0x4f7ffffe, v3
	v_cvt_u32_f32_e32 v3, v3
	v_mul_lo_u32 v4, v4, v3
	v_mul_hi_u32 v4, v3, v4
	v_add_u32_e32 v3, v3, v4
	s_waitcnt vmcnt(0) lgkmcnt(0)
	v_mul_hi_u32 v3, v1, v3
	v_mul_lo_u32 v5, v3, v2
	v_add_u32_e32 v4, 1, v1
	v_sub_u32_e32 v1, v1, v5
	v_add_u32_e32 v6, 1, v3
	v_cmp_ge_u32_e32 vcc, v1, v2
	v_sub_u32_e32 v5, v1, v2
	s_nop 0
	v_cndmask_b32_e32 v3, v3, v6, vcc
	v_cndmask_b32_e32 v1, v1, v5, vcc
	v_add_u32_e32 v5, 1, v3
	v_cmp_ge_u32_e32 vcc, v1, v2
	s_nop 1
	v_cndmask_b32_e32 v1, v3, v5, vcc
	v_mad_u64_u32 v[2:3], s[4:5], v2, v1, v[2:3]
	v_cmp_ne_u32_e32 vcc, v4, v2
	s_and_saveexec_b64 s[4:5], vcc
	s_xor_b64 s[4:5], exec, s[4:5]
	s_cbranch_execz .LBB0_233
	s_add_i32 s6, s0, 0x900
	s_lshl_b64 s[6:7], s[6:7], 2
	s_add_u32 s8, s40, 0x3500
	s_addc_u32 s9, s41, 0
	v_mov_b64_e32 v[2:3], s[8:9]
	flat_load_dword v0, v[2:3] sc1
	s_waitcnt vmcnt(0) lgkmcnt(0)
	v_cmp_eq_u32_e32 vcc, v0, v1
	s_and_saveexec_b64 s[6:7], vcc
	s_cbranch_execz .LBB0_232
	s_mov_b32 s1, 1
	s_mov_b64 s[10:11], 0
	s_branch .LBB0_224

; __device__ __forceinline__ unsigned xb_add(unsigned* p, unsigned v) { return __hip_atomic_fetch_add(p, v, __ATOMIC_RELAXED, __HIP_MEMORY_SCOPE_AGENT); }
; __device__ __forceinline__ void xcd_barrier(const XcdBarrier& b, const int wv) {
;     ...
;             __builtin_amdgcn_fence(__ATOMIC_ACQUIRE, "agent");
;             xb_add(&bar[XB_XGEN(bx)], 1u);
;             asm volatile("s_waitcnt vmcnt(0)" ::: "memory");
.LBB0_248:
	s_or_b64 exec, exec, s[6:7]
	s_addk_i32 s0, 0x900
	s_mov_b32 s1, 0
	s_lshl_b64 s[0:1], s[0:1], 2
	s_add_u32 s0, s40, s0
	s_addc_u32 s1, s41, s1
	v_mov_b32_e32 v2, 1
	v_mov_b64_e32 v[0:1], s[0:1]
	s_waitcnt vmcnt(0) lgkmcnt(0)
	buffer_inv sc1
	s_waitcnt vmcnt(0)

; __device__ __forceinline__ unsigned xb_add(unsigned* p, unsigned v) { return __hip_atomic_fetch_add(p, v, __ATOMIC_RELAXED, __HIP_MEMORY_SCOPE_AGENT); }
; __device__ __forceinline__ void xcd_barrier(const XcdBarrier& b, const int wv) {
;     ...
;             __builtin_amdgcn_fence(__ATOMIC_ACQUIRE, "agent");
;             xb_add(&bar[XB_XGEN(bx)], 1u);
;             asm volatile("s_waitcnt vmcnt(0)" ::: "memory");
.LBB0_251:
	s_or_b64 exec, exec, s[4:5]
	s_add_i32 s40, s24, 0x900
	s_lshl_b64 s[4:5], s[40:41], 2
	s_add_u32 s4, s42, s4
	s_addc_u32 s5, s43, s5
	v_mov_b64_e32 v[0:1], s[4:5]
	s_waitcnt vmcnt(0) lgkmcnt(0)
	buffer_inv sc1
	s_waitcnt vmcnt(0)

; __device__ __forceinline__ unsigned xb_ld(unsigned* p)              { return __hip_atomic_load(p, __ATOMIC_RELAXED, __HIP_MEMORY_SCOPE_AGENT); }
; __device__ __forceinline__ unsigned xb_add(unsigned* p, unsigned v) { return __hip_atomic_fetch_add(p, v, __ATOMIC_RELAXED, __HIP_MEMORY_SCOPE_AGENT); }
; #define XB_SPIN(cond, bar) do { unsigned _sp = 0; while (cond) { __builtin_amdgcn_s_sleep(1); \
;     if ((++_sp & 255u) == 0u) { if (xb_ld(&(bar)[XB_TMO])) break; if (_sp > XB_SPIN_CAP) { atomicAdd(&(bar)[XB_TMO], 1u); break; } } } } while (0)
; __device__ __forceinline__ void xcd_barrier(const XcdBarrier& b, const int wv) {
;     ...
;         const unsigned old = xb_add(&bar[XB_XSUB(bx)], 1u);
;         const unsigned gen = old / nloc;
;         if (old + 1u == (gen + 1u) * nloc) {
;             __builtin_amdgcn_fence(__ATOMIC_RELEASE, "agent");
;             asm volatile("s_waitcnt vmcnt(0)" ::: "memory");
;             const unsigned og = xb_add(&bar[XB_TOP], 1u);
;             const unsigned tg = og / nx;
;             if (og + 1u == (tg + 1u) * nx) xb_add(&bar[XB_TOPGEN], 1u);
;             else XB_SPIN(xb_ld(&bar[XB_TOPGEN]) == tg, bar);
;             __builtin_amdgcn_fence(__ATOMIC_ACQUIRE, "agent");
;             xb_add(&bar[XB_XGEN(bx)], 1u);
;             asm volatile("s_waitcnt vmcnt(0)" ::: "memory");
;         } else {
;             XB_SPIN(xb_ld(&bar[XB_XGEN(bx)]) == gen, bar);
.LBB0_291:
	s_lshl_b32 s24, s33, 6
	s_add_i32 s40, s24, 0x500
	s_lshl_b64 s[4:5], s[40:41], 2
	s_add_u32 s4, s42, s4
	s_addc_u32 s5, s43, s5
	v_mov_b64_e32 v[4:5], s[4:5]
	flat_atomic_add v3, v[4:5], v243 sc0
	v_cvt_f32_u32_e32 v1, v2
	v_sub_u32_e32 v4, 0, v2
	v_rcp_iflag_f32_e32 v1, v1
	s_nop 0
	v_mul_f32_e32 v1, 0x4f7ffffe, v1
	v_cvt_u32_f32_e32 v1, v1
	v_mul_lo_u32 v4, v4, v1
	v_mul_hi_u32 v4, v1, v4
	v_add_u32_e32 v1, v1, v4
	s_waitcnt vmcnt(0) lgkmcnt(0)
	v_mul_hi_u32 v1, v3, v1
	v_mul_lo_u32 v4, v1, v2
	v_sub_u32_e32 v4, v3, v4
	v_cmp_ge_u32_e32 vcc, v4, v2
	v_add_u32_e32 v5, 1, v1
	s_nop 0
	v_cndmask_b32_e32 v1, v1, v5, vcc
	v_sub_u32_e32 v5, v4, v2
	v_cndmask_b32_e32 v4, v4, v5, vcc
	v_cmp_ge_u32_e32 vcc, v4, v2
	v_add_u32_e32 v4, 1, v1
	s_nop 0
	v_cndmask_b32_e32 v1, v1, v4, vcc
	v_add_u32_e32 v4, 1, v3
	v_mad_u64_u32 v[2:3], s[4:5], v2, v1, v[2:3]
	v_cmp_ne_u32_e32 vcc, v4, v2
	s_and_saveexec_b64 s[4:5], vcc
	s_xor_b64 s[4:5], exec, s[4:5]
	s_cbranch_execz .LBB0_304
	s_add_i32 s40, s24, 0x900
	s_lshl_b64 s[6:7], s[40:41], 2
	s_add_u32 s8, s42, 0x3500
	s_addc_u32 s9, s43, 0
	v_mov_b64_e32 v[2:3], s[8:9]
	flat_load_dword v0, v[2:3] sc1
	s_waitcnt vmcnt(0) lgkmcnt(0)
	v_cmp_eq_u32_e32 vcc, v0, v1
	s_and_saveexec_b64 s[6:7], vcc
	s_cbranch_execz .LBB0_303
	s_mov_b32 s25, 1
	s_mov_b64 s[10:11], 0
	s_branch .LBB0_295

; __device__ __forceinline__ unsigned xb_ld(unsigned* p)              { return __hip_atomic_load(p, __ATOMIC_RELAXED, __HIP_MEMORY_SCOPE_AGENT); }
; __device__ __forceinline__ unsigned xb_add(unsigned* p, unsigned v) { return __hip_atomic_fetch_add(p, v, __ATOMIC_RELAXED, __HIP_MEMORY_SCOPE_AGENT); }
; #define XB_SPIN(cond, bar) do { unsigned _sp = 0; while (cond) { __builtin_amdgcn_s_sleep(1); \
;     if ((++_sp & 255u) == 0u) { if (xb_ld(&(bar)[XB_TMO])) break; if (_sp > XB_SPIN_CAP) { atomicAdd(&(bar)[XB_TMO], 1u); break; } } } } while (0)
; __device__ __forceinline__ void xcd_barrier(const XcdBarrier& b, const int wv) {
;     ...
;         const unsigned old = xb_add(&bar[XB_XSUB(bx)], 1u);
;         const unsigned gen = old / nloc;
;         if (old + 1u == (gen + 1u) * nloc) {
;             __builtin_amdgcn_fence(__ATOMIC_RELEASE, "agent");
;             asm volatile("s_waitcnt vmcnt(0)" ::: "memory");
;             const unsigned og = xb_add(&bar[XB_TOP], 1u);
;             const unsigned tg = og / nx;
;             if (og + 1u == (tg + 1u) * nx) xb_add(&bar[XB_TOPGEN], 1u);
;             else XB_SPIN(xb_ld(&bar[XB_TOPGEN]) == tg, bar);
;             __builtin_amdgcn_fence(__ATOMIC_ACQUIRE, "agent");
;             xb_add(&bar[XB_XGEN(bx)], 1u);
;             asm volatile("s_waitcnt vmcnt(0)" ::: "memory");
;         } else {
;             XB_SPIN(xb_ld(&bar[XB_XGEN(bx)]) == gen, bar);
.LBB0_515:
	s_lshl_b32 s4, s4, 6
	s_add_i32 s40, s4, 0x500
	s_lshl_b64 s[6:7], s[40:41], 2
	s_add_u32 s6, s44, s6
	s_addc_u32 s7, s45, s7
	v_mov_b64_e32 v[4:5], s[6:7]
	flat_atomic_add v3, v[4:5], v243 sc0
	v_cvt_f32_u32_e32 v1, v2
	v_sub_u32_e32 v4, 0, v2
	v_rcp_iflag_f32_e32 v1, v1
	s_nop 0
	v_mul_f32_e32 v1, 0x4f7ffffe, v1
	v_cvt_u32_f32_e32 v1, v1
	v_mul_lo_u32 v4, v4, v1
	v_mul_hi_u32 v4, v1, v4
	v_add_u32_e32 v1, v1, v4
	s_waitcnt vmcnt(0) lgkmcnt(0)
	v_mul_hi_u32 v1, v3, v1
	v_mul_lo_u32 v4, v1, v2
	v_sub_u32_e32 v4, v3, v4
	v_cmp_ge_u32_e32 vcc, v4, v2
	v_add_u32_e32 v5, 1, v1
	s_nop 0
	v_cndmask_b32_e32 v1, v1, v5, vcc
	v_sub_u32_e32 v5, v4, v2
	v_cndmask_b32_e32 v4, v4, v5, vcc
	v_cmp_ge_u32_e32 vcc, v4, v2
	v_add_u32_e32 v4, 1, v1
	s_nop 0
	v_cndmask_b32_e32 v1, v1, v4, vcc
	v_add_u32_e32 v4, 1, v3
	v_mad_u64_u32 v[2:3], s[6:7], v2, v1, v[2:3]
	v_cmp_ne_u32_e32 vcc, v4, v2
	s_and_saveexec_b64 s[6:7], vcc
	s_xor_b64 s[6:7], exec, s[6:7]
	s_cbranch_execz .LBB0_528
	s_add_i32 s40, s4, 0x900
	s_lshl_b64 s[8:9], s[40:41], 2
	s_add_u32 s10, s44, 0x3500
	s_addc_u32 s11, s45, 0
	v_mov_b64_e32 v[2:3], s[10:11]
	flat_load_dword v0, v[2:3] sc1
	s_waitcnt vmcnt(0) lgkmcnt(0)
	v_cmp_eq_u32_e32 vcc, v0, v1
	s_and_saveexec_b64 s[8:9], vcc
	s_cbranch_execz .LBB0_527
	s_mov_b32 s5, 1
	s_mov_b64 s[12:13], 0
	s_branch .LBB0_519

; __device__ __forceinline__ unsigned xb_add(unsigned* p, unsigned v) { return __hip_atomic_fetch_add(p, v, __ATOMIC_RELAXED, __HIP_MEMORY_SCOPE_AGENT); }
; __device__ __forceinline__ void xcd_barrier(const XcdBarrier& b, const int wv) {
;     ...
;             __builtin_amdgcn_fence(__ATOMIC_ACQUIRE, "agent");
;             xb_add(&bar[XB_XGEN(bx)], 1u);
;             asm volatile("s_waitcnt vmcnt(0)" ::: "memory");
.LBB0_543:
	s_or_b64 exec, exec, s[6:7]
	s_add_i32 s40, s4, 0x900
	s_lshl_b64 s[4:5], s[40:41], 2
	s_add_u32 s4, s44, s4
	s_addc_u32 s5, s45, s5
	v_mov_b64_e32 v[0:1], s[4:5]
	s_waitcnt vmcnt(0) lgkmcnt(0)
	buffer_inv sc1
	s_waitcnt vmcnt(0)

; __device__ __forceinline__ unsigned xb_ld(unsigned* p)              { return __hip_atomic_load(p, __ATOMIC_RELAXED, __HIP_MEMORY_SCOPE_AGENT); }
; __device__ __forceinline__ unsigned xb_add(unsigned* p, unsigned v) { return __hip_atomic_fetch_add(p, v, __ATOMIC_RELAXED, __HIP_MEMORY_SCOPE_AGENT); }
; #define XB_SPIN(cond, bar) do { unsigned _sp = 0; while (cond) { __builtin_amdgcn_s_sleep(1); \
;     if ((++_sp & 255u) == 0u) { if (xb_ld(&(bar)[XB_TMO])) break; if (_sp > XB_SPIN_CAP) { atomicAdd(&(bar)[XB_TMO], 1u); break; } } } } while (0)
; __device__ __forceinline__ void xcd_barrier(const XcdBarrier& b, const int wv) {
;     ...
;         const unsigned old = xb_add(&bar[XB_XSUB(bx)], 1u);
;         const unsigned gen = old / nloc;
;         if (old + 1u == (gen + 1u) * nloc) {
;             __builtin_amdgcn_fence(__ATOMIC_RELEASE, "agent");
;             asm volatile("s_waitcnt vmcnt(0)" ::: "memory");
;             const unsigned og = xb_add(&bar[XB_TOP], 1u);
;             const unsigned tg = og / nx;
;             if (og + 1u == (tg + 1u) * nx) xb_add(&bar[XB_TOPGEN], 1u);
;             else XB_SPIN(xb_ld(&bar[XB_TOPGEN]) == tg, bar);
;             __builtin_amdgcn_fence(__ATOMIC_ACQUIRE, "agent");
;             xb_add(&bar[XB_XGEN(bx)], 1u);
;             asm volatile("s_waitcnt vmcnt(0)" ::: "memory");
;         } else {
;             XB_SPIN(xb_ld(&bar[XB_XGEN(bx)]) == gen, bar);
.LBB0_591:
	s_lshl_b32 s4, s4, 6
	s_add_i32 s40, s4, 0x500
	s_lshl_b64 s[6:7], s[40:41], 2
	s_add_u32 s6, s46, s6
	s_addc_u32 s7, s47, s7
	v_mov_b64_e32 v[4:5], s[6:7]
	flat_atomic_add v3, v[4:5], v243 sc0
	v_cvt_f32_u32_e32 v1, v2
	v_sub_u32_e32 v4, 0, v2
	v_rcp_iflag_f32_e32 v1, v1
	s_nop 0
	v_mul_f32_e32 v1, 0x4f7ffffe, v1
	v_cvt_u32_f32_e32 v1, v1
	v_mul_lo_u32 v4, v4, v1
	v_mul_hi_u32 v4, v1, v4
	v_add_u32_e32 v1, v1, v4
	s_waitcnt vmcnt(0) lgkmcnt(0)
	v_mul_hi_u32 v1, v3, v1
	v_mul_lo_u32 v4, v1, v2
	v_sub_u32_e32 v4, v3, v4
	v_cmp_ge_u32_e32 vcc, v4, v2
	v_add_u32_e32 v5, 1, v1
	s_nop 0
	v_cndmask_b32_e32 v1, v1, v5, vcc
	v_sub_u32_e32 v5, v4, v2
	v_cndmask_b32_e32 v4, v4, v5, vcc
	v_cmp_ge_u32_e32 vcc, v4, v2
	v_add_u32_e32 v4, 1, v1
	s_nop 0
	v_cndmask_b32_e32 v1, v1, v4, vcc
	v_add_u32_e32 v4, 1, v3
	v_mad_u64_u32 v[2:3], s[6:7], v2, v1, v[2:3]
	v_cmp_ne_u32_e32 vcc, v4, v2
	s_and_saveexec_b64 s[6:7], vcc
	s_xor_b64 s[6:7], exec, s[6:7]
	s_cbranch_execz .LBB0_604
	s_add_i32 s40, s4, 0x900
	s_lshl_b64 s[8:9], s[40:41], 2
	s_add_u32 s10, s46, 0x3500
	s_addc_u32 s11, s47, 0
	v_mov_b64_e32 v[2:3], s[10:11]
	flat_load_dword v0, v[2:3] sc1
	s_waitcnt vmcnt(0) lgkmcnt(0)
	v_cmp_eq_u32_e32 vcc, v0, v1
	s_and_saveexec_b64 s[8:9], vcc
	s_cbranch_execz .LBB0_603
	s_mov_b32 s5, 1
	s_mov_b64 s[12:13], 0
	s_branch .LBB0_595

; __device__ __forceinline__ unsigned xb_add(unsigned* p, unsigned v) { return __hip_atomic_fetch_add(p, v, __ATOMIC_RELAXED, __HIP_MEMORY_SCOPE_AGENT); }
; __device__ __forceinline__ void xcd_barrier(const XcdBarrier& b, const int wv) {
;     ...
;             __builtin_amdgcn_fence(__ATOMIC_ACQUIRE, "agent");
;             xb_add(&bar[XB_XGEN(bx)], 1u);
;             asm volatile("s_waitcnt vmcnt(0)" ::: "memory");
.LBB0_619:
	s_or_b64 exec, exec, s[6:7]
	s_add_i32 s40, s4, 0x900
	s_lshl_b64 s[4:5], s[40:41], 2
	s_add_u32 s4, s46, s4
	s_addc_u32 s5, s47, s5
	v_mov_b64_e32 v[0:1], s[4:5]
	s_waitcnt vmcnt(0) lgkmcnt(0)
	buffer_inv sc1
	s_waitcnt vmcnt(0)

; __device__ __forceinline__ unsigned xb_add(unsigned* p, unsigned v) { return __hip_atomic_fetch_add(p, v, __ATOMIC_RELAXED, __HIP_MEMORY_SCOPE_AGENT); }
; __device__ __forceinline__ void xcd_barrier(const XcdBarrier& b, const int wv) {
;     ...
;             __builtin_amdgcn_fence(__ATOMIC_ACQUIRE, "agent");
;             xb_add(&bar[XB_XGEN(bx)], 1u);
;             asm volatile("s_waitcnt vmcnt(0)" ::: "memory");
.LBB0_736:
	s_or_b64 exec, exec, s[8:9]
	s_add_i32 s40, s4, 0x900
	s_lshl_b64 s[4:5], s[40:41], 2
	s_add_u32 s4, s44, s4
	s_addc_u32 s5, s45, s5
	v_mov_b64_e32 v[0:1], s[4:5]
	s_waitcnt vmcnt(0) lgkmcnt(0)
	buffer_inv sc1
	s_waitcnt vmcnt(0)
